# static s_setprio 1 for waves 4-7 in the attention main loop, per-MFMA toggles removed (strategy 7.4)
# baseline (speedup 1.0000x reference)
.LBB0_198:
	v_or_b32_e32 v0, s61, v98
	v_readlane_b32 s68, v254, 23
	v_ashrrev_i32_e32 v1, 31, v0
	v_readlane_b32 s80, v254, 35
	v_readlane_b32 s81, v254, 36
	s_lshr_b32 s15, s54, 2
	s_and_b32 s14, s15, s14
	v_lshl_add_u64 v[0:1], v[0:1], 2, s[80:81]
	global_load_dword v2, v[0:1], off
	s_and_b32 s15, s5, 1
	s_lshl_b32 s5, s16, 12
	s_lshl_b32 s18, s54, 6
	s_add_i32 s24, s5, 0x8000
	s_lshl_b32 s5, s15, 8
	s_and_b32 s18, s18, 0xc0
	s_or_b32 s5, s5, s18
	s_lshl_b32 s17, s16, 13
	s_lshl_b32 s18, s5, 1
	s_add_u32 s18, s58, s18
	s_addc_u32 s19, s59, 0
	s_lshl_b32 s15, s15, 7
	v_readlane_b32 s26, v255, 10
	v_readlane_b32 s27, v255, 11
	s_add_u32 s54, s26, s15
	s_addc_u32 s55, s27, 0
	v_readlane_b32 s26, v255, 6
	v_readlane_b32 s27, v255, 7
	s_add_u32 s56, s26, s15
	s_addc_u32 s57, s27, 0
	s_lshl_b32 s14, s14, 8
	s_cmp_lt_i32 s16, 8
	s_cselect_b32 s16, s17, s24
	v_ashrrev_i32_e32 v0, 1, v97
	s_movk_i32 s15, 0xffe0
	v_and_or_b32 v0, v0, s15, v195
	s_cselect_b32 s15, 0x7d, 61
	s_add_i32 s14, s16, s14
	v_add_u32_e32 v0, s14, v0
	v_ashrrev_i32_e32 v1, 31, v0
	v_lshlrev_b64 v[0:1], 10, v[0:1]
	v_lshl_add_u64 v[0:1], s[18:19], 0, v[0:1]
	v_lshlrev_b32_e32 v168, 4, v193
	v_lshl_add_u64 v[0:1], v[0:1], 0, v[168:169]
	global_load_dwordx4 v[120:123], v[0:1], off
	global_load_dwordx4 v[116:119], v[0:1], off offset:32
	global_load_dwordx4 v[112:115], v[0:1], off offset:64
	global_load_dwordx4 v[124:127], v[0:1], off offset:96
	v_and_b32_e32 v3, 64, v182
	s_waitcnt vmcnt(10)
	v_xor_b32_e32 v4, 32, v182
	v_add_u32_e32 v3, 64, v3
	v_cmp_lt_i32_e32 vcc, v4, v3
	v_xor_b32_e32 v5, 16, v182
	v_xor_b32_e32 v6, 8, v182
	v_cndmask_b32_e32 v4, v182, v4, vcc
	v_cmp_lt_i32_e32 vcc, v5, v3
	v_lshlrev_b32_e32 v168, 2, v4
	v_xor_b32_e32 v7, 4, v182
	v_cndmask_b32_e32 v5, v182, v5, vcc
	v_cmp_lt_i32_e32 vcc, v6, v3
	s_waitcnt vmcnt(8)
	v_xor_b32_e32 v8, 2, v182
	v_xor_b32_e32 v9, 1, v182
	v_cndmask_b32_e32 v6, v182, v6, vcc
	v_cmp_lt_i32_e32 vcc, v7, v3
	v_ashrrev_i32_e32 v10, 3, v97
	v_and_b32_e32 v11, 7, v97
	v_cndmask_b32_e32 v7, v182, v7, vcc
	v_cmp_lt_i32_e32 vcc, v8, v3
	v_lshlrev_b32_e32 v11, 4, v11
	v_lshlrev_b32_e32 v60, 7, v195
	v_cndmask_b32_e32 v0, v182, v8, vcc
	v_cmp_lt_i32_e32 vcc, v9, v3
	s_waitcnt vmcnt(6)
	v_lshlrev_b32_e32 v12, 2, v0
	v_lshlrev_b32_e32 v3, 2, v5
	v_cndmask_b32_e32 v1, v182, v9, vcc
	v_lshlrev_b32_e32 v13, 2, v1
	v_lshlrev_b32_e32 v8, 2, v6
	v_lshlrev_b32_e32 v9, 2, v7
	v_lshlrev_b32_e32 v64, 4, v97
	v_bfe_u32 v61, v97, 1, 3
	v_and_b32_e32 v200, 0xc0, v64
	v_mov_b32_e32 v197, 0
	s_mov_b32 s17, 0
	v_readlane_b32 s69, v254, 24
	v_readlane_b32 s70, v254, 25
	v_readlane_b32 s71, v254, 26
	v_readlane_b32 s72, v254, 27
	v_readlane_b32 s73, v254, 28
	v_readlane_b32 s74, v254, 29
	v_readlane_b32 s75, v254, 30
	s_waitcnt vmcnt(4)
	v_and_b32_e32 v4, 0x7fffffff, v2
	ds_bpermute_b32 v4, v168, v4
	v_max_f32_e64 v0, |v2|, |v2|
	v_readlane_b32 s76, v254, 31
	v_readlane_b32 s77, v254, 32
	v_readlane_b32 s78, v254, 33
	s_waitcnt lgkmcnt(0)
	v_max_f32_e32 v1, v4, v4
	v_max_f32_e32 v14, v0, v1
	v_add_u32_e32 v0, s16, v10
	v_lshl_or_b32 v198, v0, 8, v11
	ds_bpermute_b32 v15, v3, v14
	global_load_dwordx4 v[0:3], v198, s[54:55]
	global_load_dwordx4 v[4:7], v198, s[56:57]
	v_add_u32_e32 v204, 0x4000, v198
	global_load_dwordx4 v[48:51], v204, s[54:55]
	s_mov_b32 s16, 0xf800000
	s_waitcnt lgkmcnt(0)
	v_max_f32_e32 v11, v15, v15
	v_max_f32_e32 v11, v14, v11
	ds_bpermute_b32 v8, v8, v11
	v_readlane_b32 s79, v254, 34
	v_readlane_b32 s82, v254, 37
	v_readlane_b32 s83, v254, 38
	s_waitcnt lgkmcnt(0)
	v_max_f32_e32 v8, v8, v8
	v_max_f32_e32 v8, v11, v8
	ds_bpermute_b32 v9, v9, v8
	s_waitcnt lgkmcnt(0)
	v_max_f32_e32 v9, v9, v9
	v_max_f32_e32 v8, v8, v9
	ds_bpermute_b32 v9, v12, v8
	s_waitcnt vmcnt(6)
	v_and_b32_e32 v15, 0xffff0000, v120
	v_lshlrev_b32_e32 v14, 16, v120
	v_mul_f32_e32 v15, v15, v15
	v_lshlrev_b32_e32 v16, 16, v121
	v_fmac_f32_e32 v15, v14, v14
	v_and_b32_e32 v17, 0xffff0000, v121
	v_fmac_f32_e32 v15, v16, v16
	v_lshlrev_b32_e32 v18, 16, v122
	v_fmac_f32_e32 v15, v17, v17
	v_and_b32_e32 v19, 0xffff0000, v122
	v_fmac_f32_e32 v15, v18, v18
	v_lshlrev_b32_e32 v20, 16, v123
	v_fmac_f32_e32 v15, v19, v19
	v_and_b32_e32 v21, 0xffff0000, v123
	v_fmac_f32_e32 v15, v20, v20
	s_waitcnt vmcnt(5)
	v_lshlrev_b32_e32 v22, 16, v116
	v_fmac_f32_e32 v15, v21, v21
	v_and_b32_e32 v23, 0xffff0000, v116
	v_fmac_f32_e32 v15, v22, v22
	v_lshlrev_b32_e32 v24, 16, v117
	v_fmac_f32_e32 v15, v23, v23
	v_and_b32_e32 v25, 0xffff0000, v117
	v_fmac_f32_e32 v15, v24, v24
	v_lshlrev_b32_e32 v26, 16, v118
	v_fmac_f32_e32 v15, v25, v25
	v_and_b32_e32 v27, 0xffff0000, v118
	v_fmac_f32_e32 v15, v26, v26
	v_lshlrev_b32_e32 v28, 16, v119
	v_fmac_f32_e32 v15, v27, v27
	s_waitcnt lgkmcnt(0)
	v_max_f32_e32 v9, v9, v9
	v_fmac_f32_e32 v15, v28, v28
	v_max_f32_e32 v11, v8, v9
	v_and_b32_e32 v8, 0xffff0000, v119
	v_fmac_f32_e32 v15, v8, v8
	s_waitcnt vmcnt(4)
	v_lshlrev_b32_e32 v8, 16, v112
	v_fmac_f32_e32 v15, v8, v8
	v_and_b32_e32 v8, 0xffff0000, v112
	v_fmac_f32_e32 v15, v8, v8
	v_lshlrev_b32_e32 v8, 16, v113
	v_fmac_f32_e32 v15, v8, v8
	v_and_b32_e32 v8, 0xffff0000, v113
	v_fmac_f32_e32 v15, v8, v8
	v_lshlrev_b32_e32 v8, 16, v114
	v_fmac_f32_e32 v15, v8, v8
	v_and_b32_e32 v8, 0xffff0000, v114
	v_fmac_f32_e32 v15, v8, v8
	v_lshlrev_b32_e32 v8, 16, v115
	v_fmac_f32_e32 v15, v8, v8
	v_and_b32_e32 v8, 0xffff0000, v115
	v_fmac_f32_e32 v15, v8, v8
	s_waitcnt vmcnt(3)
	v_and_b32_e32 v9, 0xffff0000, v124
	v_lshlrev_b32_e32 v8, 16, v124
	v_pk_mul_f32 v[8:9], v[8:9], v[8:9]
	ds_bpermute_b32 v12, v13, v11
	v_add_f32_e32 v8, v8, v15
	v_add_f32_e32 v13, v9, v8
	v_and_b32_e32 v9, 0xffff0000, v125
	v_lshlrev_b32_e32 v8, 16, v125
	v_pk_mul_f32 v[8:9], v[8:9], v[8:9]
	v_lshrrev_b32_e32 v15, 1, v97
	v_add_f32_e32 v8, v8, v13
	v_add_f32_e32 v13, v9, v8
	v_and_b32_e32 v9, 0xffff0000, v126
	v_lshlrev_b32_e32 v8, 16, v126
	v_pk_mul_f32 v[8:9], v[8:9], v[8:9]
	v_bitop3_b32 v15, v193, v15, 7 bitop3:0x78
	v_add_f32_e32 v8, v8, v13
	v_add_f32_e32 v13, v9, v8
	v_and_b32_e32 v9, 0xffff0000, v127
	v_lshlrev_b32_e32 v8, 16, v127
	v_pk_mul_f32 v[8:9], v[8:9], v[8:9]
	v_lshl_or_b32 v201, v15, 4, v60
	v_add_f32_e32 v8, v8, v13
	v_add_f32_e32 v8, v9, v8
	ds_bpermute_b32 v9, v168, v8
	s_waitcnt lgkmcnt(1)
	v_max_f32_e32 v12, v12, v12
	v_max_f32_e32 v11, v11, v12
	v_lshlrev_b32_e32 v12, 10, v97
	v_and_b32_e32 v13, 48, v64
	s_waitcnt lgkmcnt(0)
	v_add_f32_e32 v8, v8, v9
	v_mul_f32_e32 v14, 0x4f800000, v8
	v_cmp_gt_f32_e32 vcc, s16, v8
	v_lshrrev_b32_e32 v9, 1, v10
	v_xor_b32_e32 v9, v9, v97
	v_cndmask_b32_e32 v8, v8, v14, vcc
	v_sqrt_f32_e32 v14, v8
	v_lshlrev_b32_e32 v9, 4, v9
	s_movk_i32 s16, 0x70
	v_and_b32_e32 v12, 0x1000, v12
	v_add_u32_e32 v15, -1, v14
	v_fma_f32 v16, -v15, v14, v8
	v_cmp_ge_f32_e64 s[42:43], 0, v16
	v_add_u32_e32 v16, 1, v14
	v_mul_f32_e32 v11, 0x41000000, v11
	v_cndmask_b32_e64 v15, v14, v15, s[42:43]
	v_fma_f32 v14, -v16, v14, v8
	v_cmp_lt_f32_e64 s[42:43], 0, v14
	v_mul_f32_e32 v11, 0xbf8147ae, v11
	s_nop 0
	v_cndmask_b32_e64 v14, v15, v16, s[42:43]
	v_mul_f32_e32 v15, 0x37800000, v14
	v_cndmask_b32_e32 v14, v14, v15, vcc
	v_cmp_class_f32_e32 vcc, v8, v173
	s_nop 1
	v_cndmask_b32_e32 v8, v14, v8, vcc
	v_lshlrev_b32_e32 v14, 7, v10
	v_and_or_b32 v202, v9, s16, v14
	s_waitcnt vmcnt(2)
	ds_write_b128 v202, v[0:3]
	v_lshl_or_b32 v0, v10, 6, v13
	v_add_u32_e32 v196, v0, v12
	s_waitcnt vmcnt(1)
	ds_write_b128 v196, v[4:7] offset:16384
	s_waitcnt lgkmcnt(0)
	s_barrier
	ds_read_b128 v[0:3], v201
	ds_read_b128 v[52:55], v201 offset:4096
	v_mul_f32_e32 v32, v11, v8
	v_mov_b32_e32 v33, v32
	v_mov_b32_e32 v34, v32
	v_mov_b32_e32 v35, v32
	v_mov_b32_e32 v36, v32
	v_mov_b32_e32 v37, v32
	v_mov_b32_e32 v38, v32
	v_mov_b32_e32 v39, v32
	v_mov_b32_e32 v40, v32
	v_mov_b32_e32 v41, v32
	v_mov_b32_e32 v42, v32
	v_mov_b32_e32 v43, v32
	v_mov_b32_e32 v44, v32
	v_mov_b32_e32 v45, v32
	v_mov_b32_e32 v46, v32
	v_mov_b32_e32 v47, v32
	s_mov_b32 s16, 0
	s_waitcnt lgkmcnt(1)
	v_mfma_f32_32x32x16_bf16 v[16:31], v[0:3], v[120:123], v[32:47]
	v_bitop3_b32 v0, v193, v61, 2 bitop3:0x36
	v_lshl_or_b32 v206, v0, 4, v60
	s_waitcnt lgkmcnt(0)
	v_mfma_f32_32x32x16_bf16 v[0:15], v[52:55], v[120:123], v[32:47]
	ds_read_b128 v[52:55], v206
	ds_read_b128 v[56:59], v206 offset:4096
	s_waitcnt lgkmcnt(1)
	v_mfma_f32_32x32x16_bf16 v[16:31], v[52:55], v[116:119], v[16:31]
	v_bitop3_b32 v52, v193, v61, 4 bitop3:0x36
	v_lshl_or_b32 v203, v52, 4, v60
	s_waitcnt lgkmcnt(0)
	v_mfma_f32_32x32x16_bf16 v[0:15], v[56:59], v[116:119], v[0:15]
	ds_read_b128 v[52:55], v203
	ds_read_b128 v[56:59], v203 offset:4096
	s_waitcnt lgkmcnt(1)
	v_mfma_f32_32x32x16_bf16 v[16:31], v[52:55], v[112:115], v[16:31]
	v_bitop3_b32 v52, v193, v61, 6 bitop3:0x36
	v_lshl_or_b32 v205, v52, 4, v60
	s_waitcnt lgkmcnt(0)
	v_mfma_f32_32x32x16_bf16 v[0:15], v[56:59], v[112:115], v[0:15]
	ds_read_b128 v[52:55], v205
	ds_read_b128 v[56:59], v205 offset:4096
	s_waitcnt vmcnt(0)
	ds_write_b128 v202, v[48:51] offset:8192
	s_waitcnt lgkmcnt(0)
	s_barrier
	v_mfma_f32_32x32x16_bf16 v[16:31], v[52:55], v[124:127], v[16:31]
	v_mfma_f32_32x32x16_bf16 v[0:15], v[56:59], v[124:127], v[0:15]
	s_nop 10
	v_exp_f32_e32 v48, v16
	v_exp_f32_e32 v49, v17
	v_exp_f32_e32 v50, v18
	v_exp_f32_e32 v51, v19
	v_exp_f32_e32 v52, v20
	v_exp_f32_e32 v53, v21
	v_exp_f32_e32 v54, v22
	v_exp_f32_e32 v55, v23
	v_exp_f32_e32 v56, v24
	v_exp_f32_e32 v57, v25
	v_exp_f32_e32 v58, v26
	v_exp_f32_e32 v59, v27
	v_exp_f32_e32 v60, v28
	v_exp_f32_e32 v61, v29
	v_exp_f32_e32 v62, v30
	v_exp_f32_e32 v63, v31
	v_exp_f32_e32 v162, v0
	v_exp_f32_e32 v164, v1
	v_exp_f32_e32 v165, v2
	v_exp_f32_e32 v163, v3
	v_exp_f32_e32 v156, v4
	v_exp_f32_e32 v160, v5
	v_exp_f32_e32 v161, v6
	v_exp_f32_e32 v157, v7
	v_exp_f32_e32 v136, v8
	v_exp_f32_e32 v140, v9
	v_exp_f32_e32 v141, v10
	v_exp_f32_e32 v137, v11
	v_exp_f32_e32 v128, v12
	v_exp_f32_e32 v132, v13
	v_exp_f32_e32 v133, v14
	v_exp_f32_e32 v129, v15
	v_and_b32_e32 v0, 16, v97
	v_lshlrev_b32_e32 v1, 2, v98
	v_and_or_b32 v0, v1, 12, v0
	v_lshlrev_b32_e32 v199, 1, v0
	v_lshl_or_b32 v0, v193, 8, v200
	v_add_u32_e32 v207, v199, v0
	v_mov_b32_e32 v16, 0
	v_mov_b32_e32 v17, v197
	v_mov_b32_e32 v18, v197
	v_mov_b32_e32 v19, v197
	v_mov_b32_e32 v20, v197
	v_mov_b32_e32 v21, v197
	v_mov_b32_e32 v22, v197
	v_mov_b32_e32 v23, v197
	v_mov_b32_e32 v24, v197
	v_mov_b32_e32 v25, v197
	v_mov_b32_e32 v26, v197
	v_mov_b32_e32 v27, v197
	v_mov_b32_e32 v28, v197
	v_mov_b32_e32 v29, v197
	v_mov_b32_e32 v30, v197
	v_mov_b32_e32 v31, v197
	v_mov_b32_e32 v0, 0
	v_mov_b32_e32 v1, v197
	v_mov_b32_e32 v2, v197
	v_mov_b32_e32 v3, v197
	v_mov_b32_e32 v4, v197
	v_mov_b32_e32 v5, v197
	v_mov_b32_e32 v6, v197
	v_mov_b32_e32 v7, v197
	v_mov_b32_e32 v8, v197
	v_mov_b32_e32 v9, v197
	v_mov_b32_e32 v10, v197
	v_mov_b32_e32 v11, v197
	v_mov_b32_e32 v12, v197
	v_mov_b32_e32 v13, v197
	v_mov_b32_e32 v14, v197
	v_mov_b32_e32 v15, v197
	v_cmp_lt_u32_e32 vcc, 0xff, v192
	s_nop 1
	s_cbranch_vccz .Lfg_prio_skip
	s_setprio 1
.Lfg_prio_skip:
.LBB0_199:
	v_add_u32_e32 v166, s16, v198
	v_add_u32_e32 v167, 0x8000, v166
	v_add_u32_e32 v68, 0x4000, v166
	global_load_dwordx4 v[64:67], v167, s[54:55]
	s_add_i32 s17, s17, 2
	global_load_dwordx4 v[68:71], v68, s[56:57]
	ds_read_b128 v[72:75], v201 offset:8192
	ds_read_b128 v[76:79], v201 offset:12288
	ds_read_b128 v[208:211], v206 offset:8192
	ds_read_b128 v[212:215], v206 offset:12288
	s_waitcnt lgkmcnt(3)
	v_mfma_f32_32x32x16_bf16 v[96:111], v[72:75], v[120:123], v[32:47]
	v_cvt_pk_bf16_f32 v144, v48, v49
	v_add_f32_e32 v48, v48, v49
	v_add_f32_e32 v49, v50, v51
	v_add_f32_e32 v48, v48, v49
	v_cvt_pk_bf16_f32 v145, v50, v51
	v_add_f32_e32 v48, 0, v48
	s_waitcnt lgkmcnt(2)
	v_mfma_f32_32x32x16_bf16 v[80:95], v[76:79], v[120:123], v[32:47]
	v_add_f32_e32 v49, v52, v53
	v_add_f32_e32 v50, v54, v55
	v_add_f32_e32 v49, v49, v50
	v_cvt_pk_bf16_f32 v146, v52, v53
	v_cvt_pk_bf16_f32 v147, v54, v55
	v_add_f32_e32 v152, v49, v48
	ds_read_b128 v[48:51], v203 offset:8192
	ds_read_b128 v[52:55], v203 offset:12288
	ds_read_b128 v[72:75], v205 offset:8192
	ds_read_b128 v[76:79], v205 offset:12288
	s_waitcnt lgkmcnt(5)
	v_mfma_f32_32x32x16_bf16 v[96:111], v[208:211], v[116:119], v[96:111]
	v_cvt_pk_bf16_f32 v148, v56, v57
	v_add_f32_e32 v56, v56, v57
	v_add_f32_e32 v57, v58, v59
	v_add_f32_e32 v56, v56, v57
	v_cvt_pk_bf16_f32 v149, v58, v59
	v_add_f32_e32 v56, v56, v152
	s_waitcnt lgkmcnt(4)
	v_mfma_f32_32x32x16_bf16 v[80:95], v[212:215], v[116:119], v[80:95]
	v_add_f32_e32 v57, v60, v61
	v_add_f32_e32 v58, v62, v63
	v_add_f32_e32 v57, v57, v58
	v_cvt_pk_bf16_f32 v150, v60, v61
	v_cvt_pk_bf16_f32 v151, v62, v63
	v_add_f32_e32 v56, v57, v56
	s_waitcnt lgkmcnt(3)
	v_mfma_f32_32x32x16_bf16 v[96:111], v[48:51], v[112:115], v[96:111]
	v_add_f32_e64 v48, v164, v162
	v_add_f32_e64 v49, v165, v163
	v_cvt_pk_bf16_f32 v152, v162, v164
	v_add_f32_e32 v48, v48, v49
	v_cvt_pk_bf16_f32 v153, v165, v163
	v_add_f32_e32 v50, v48, v56
	s_waitcnt lgkmcnt(2)
	v_mfma_f32_32x32x16_bf16 v[80:95], v[52:55], v[112:115], v[80:95]
	v_add_f32_e64 v48, v160, v156
	v_add_f32_e64 v49, v161, v157
	v_cvt_pk_bf16_f32 v154, v156, v160
	v_add_f32_e32 v48, v48, v49
	v_cvt_pk_bf16_f32 v155, v161, v157
	v_add_f32_e32 v50, v48, v50
	s_waitcnt lgkmcnt(1)
	v_mfma_f32_32x32x16_bf16 v[96:111], v[72:75], v[124:127], v[96:111]
	v_add_f32_e64 v48, v140, v136
	v_add_f32_e64 v49, v141, v137
	v_cvt_pk_bf16_f32 v156, v136, v140
	v_add_f32_e32 v48, v48, v49
	v_cvt_pk_bf16_f32 v157, v141, v137
	v_add_f32_e32 v50, v48, v50
	s_waitcnt lgkmcnt(0)
	v_mfma_f32_32x32x16_bf16 v[80:95], v[76:79], v[124:127], v[80:95]
	v_add_f32_e64 v48, v132, v128
	v_add_f32_e64 v49, v133, v129
	v_cvt_pk_bf16_f32 v158, v128, v132
	v_add_f32_e32 v48, v48, v49
	v_cvt_pk_bf16_f32 v159, v133, v129
	v_add_f32_e32 v180, v48, v50
	ds_read_b64_tr_b16 v[48:49], v207 offset:16384
	ds_read_b64_tr_b16 v[50:51], v207 offset:16896
	ds_read_b64_tr_b16 v[52:53], v207 offset:17408
	ds_read_b64_tr_b16 v[54:55], v207 offset:17920
	ds_read_b64_tr_b16 v[56:57], v207 offset:20480
	ds_read_b64_tr_b16 v[58:59], v207 offset:20992
	ds_read_b64_tr_b16 v[60:61], v207 offset:21504
	ds_read_b64_tr_b16 v[62:63], v207 offset:22016
	s_waitcnt lgkmcnt(6)
	v_mfma_f32_32x32x16_bf16 v[16:31], v[48:51], v[144:147], v[16:31]
	v_exp_f32_e32 v96, v96
	v_exp_f32_e32 v97, v97
	v_exp_f32_e32 v98, v98
	v_exp_f32_e32 v99, v99
	s_waitcnt lgkmcnt(2)
	v_mfma_f32_32x32x16_bf16 v[0:15], v[56:59], v[144:147], v[0:15]
	v_exp_f32_e32 v100, v100
	v_exp_f32_e32 v101, v101
	v_exp_f32_e32 v102, v102
	v_exp_f32_e32 v103, v103
	ds_read_b64_tr_b16 v[48:49], v207 offset:18432
	ds_read_b64_tr_b16 v[50:51], v207 offset:18944
	ds_read_b64_tr_b16 v[56:57], v207 offset:19456
	ds_read_b64_tr_b16 v[58:59], v207 offset:19968
	ds_read_b64_tr_b16 v[72:73], v207 offset:22528
	ds_read_b64_tr_b16 v[74:75], v207 offset:23040
	ds_read_b64_tr_b16 v[76:77], v207 offset:23552
	ds_read_b64_tr_b16 v[78:79], v207 offset:24064
	v_mfma_f32_32x32x16_bf16 v[16:31], v[52:55], v[148:151], v[16:31]
	v_exp_f32_e32 v104, v104
	v_exp_f32_e32 v105, v105
	v_exp_f32_e32 v106, v106
	v_exp_f32_e32 v107, v107
	s_waitcnt lgkmcnt(8)
	v_mfma_f32_32x32x16_bf16 v[0:15], v[60:63], v[148:151], v[0:15]
	v_exp_f32_e32 v108, v108
	v_exp_f32_e32 v109, v109
	v_exp_f32_e32 v110, v110
	v_exp_f32_e32 v111, v111
	s_waitcnt lgkmcnt(6)
	v_mfma_f32_32x32x16_bf16 v[16:31], v[48:51], v[152:155], v[16:31]
	v_exp_f32_e32 v80, v80
	v_exp_f32_e32 v81, v81
	v_exp_f32_e32 v82, v82
	v_exp_f32_e32 v83, v83
	s_waitcnt lgkmcnt(2)
	v_mfma_f32_32x32x16_bf16 v[0:15], v[72:75], v[152:155], v[0:15]
	v_exp_f32_e32 v84, v84
	v_exp_f32_e32 v85, v85
	v_exp_f32_e32 v86, v86
	v_exp_f32_e32 v87, v87
	v_mfma_f32_32x32x16_bf16 v[16:31], v[56:59], v[156:159], v[16:31]
	v_exp_f32_e32 v88, v88
	v_exp_f32_e32 v89, v89
	v_exp_f32_e32 v90, v90
	v_exp_f32_e32 v91, v91
	s_waitcnt lgkmcnt(0)
	v_mfma_f32_32x32x16_bf16 v[0:15], v[76:79], v[156:159], v[0:15]
	v_exp_f32_e32 v92, v92
	v_exp_f32_e32 v93, v93
	v_exp_f32_e32 v94, v94
	v_exp_f32_e32 v95, v95
	v_add_u32_e32 v48, 0xc000, v166
	s_waitcnt vmcnt(1)
	ds_write_b128 v202, v[64:67]
	s_waitcnt vmcnt(0)
	ds_write_b128 v196, v[68:71] offset:24576
	s_waitcnt lgkmcnt(0)
	s_barrier
	global_load_dwordx4 v[160:163], v48, s[54:55]
	s_nop 0
	global_load_dwordx4 v[164:167], v167, s[56:57]
	ds_read_b128 v[64:67], v201
	ds_read_b128 v[208:211], v201 offset:4096
	ds_read_b128 v[212:215], v206
	ds_read_b128 v[216:219], v206 offset:4096
	s_waitcnt lgkmcnt(3)
	v_mfma_f32_32x32x16_bf16 v[48:63], v[64:67], v[120:123], v[32:47]
	v_add_f32_e32 v64, v96, v97
	v_add_f32_e32 v65, v98, v99
	v_add_f32_e32 v64, v64, v65
	v_cvt_pk_bf16_f32 v140, v96, v97
	v_cvt_pk_bf16_f32 v141, v98, v99
	v_add_f32_e32 v96, 0, v64
	s_waitcnt lgkmcnt(2)
	v_mfma_f32_32x32x16_bf16 v[64:79], v[208:211], v[120:123], v[32:47]
	v_add_f32_e32 v97, v100, v101
	v_add_f32_e32 v98, v102, v103
	v_add_f32_e32 v97, v97, v98
	v_cvt_pk_bf16_f32 v142, v100, v101
	v_cvt_pk_bf16_f32 v143, v102, v103
	v_add_f32_e32 v128, v97, v96
	ds_read_b128 v[96:99], v203
	ds_read_b128 v[100:103], v203 offset:4096
	ds_read_b128 v[208:211], v205
	ds_read_b128 v[220:223], v205 offset:4096
	s_waitcnt lgkmcnt(5)
	v_mfma_f32_32x32x16_bf16 v[48:63], v[212:215], v[116:119], v[48:63]
	v_cvt_pk_bf16_f32 v136, v104, v105
	v_add_f32_e32 v104, v104, v105
	v_add_f32_e32 v105, v106, v107
	v_add_f32_e32 v104, v104, v105
	v_cvt_pk_bf16_f32 v137, v106, v107
	v_add_f32_e32 v104, v104, v128
	s_waitcnt lgkmcnt(4)
	v_mfma_f32_32x32x16_bf16 v[64:79], v[216:219], v[116:119], v[64:79]
	v_add_f32_e32 v105, v108, v109
	v_add_f32_e32 v106, v110, v111
	v_add_f32_e32 v105, v105, v106
	v_cvt_pk_bf16_f32 v138, v108, v109
	v_cvt_pk_bf16_f32 v139, v110, v111
	v_add_f32_e32 v104, v105, v104
	s_waitcnt lgkmcnt(3)
	v_mfma_f32_32x32x16_bf16 v[48:63], v[96:99], v[112:115], v[48:63]
	v_cvt_pk_bf16_f32 v132, v80, v81
	v_mov_b32_e32 v96, v81
	v_mov_b32_e32 v97, v82
	v_mov_b32_e32 v81, v83
	v_pk_add_f32 v[80:81], v[96:97], v[80:81]
	v_cvt_pk_bf16_f32 v133, v82, v83
	v_add_f32_e32 v80, v80, v81
	v_add_f32_e32 v82, v80, v104
	s_waitcnt lgkmcnt(2)
	v_mfma_f32_32x32x16_bf16 v[64:79], v[100:103], v[112:115], v[64:79]
	v_cvt_pk_bf16_f32 v134, v84, v85
	v_mov_b32_e32 v80, v85
	v_mov_b32_e32 v81, v86
	v_mov_b32_e32 v85, v87
	v_pk_add_f32 v[80:81], v[80:81], v[84:85]
	v_cvt_pk_bf16_f32 v135, v86, v87
	v_add_f32_e32 v80, v80, v81
	v_add_f32_e32 v82, v80, v82
	s_waitcnt lgkmcnt(1)
	v_mfma_f32_32x32x16_bf16 v[48:63], v[208:211], v[124:127], v[48:63]
	v_cvt_pk_bf16_f32 v128, v88, v89
	v_mov_b32_e32 v80, v89
	v_mov_b32_e32 v81, v90
	v_mov_b32_e32 v89, v91
	v_pk_add_f32 v[80:81], v[80:81], v[88:89]
	v_cvt_pk_bf16_f32 v129, v90, v91
	v_add_f32_e32 v80, v80, v81
	v_add_f32_e32 v82, v80, v82
	s_waitcnt lgkmcnt(0)
	v_mfma_f32_32x32x16_bf16 v[64:79], v[220:223], v[124:127], v[64:79]
	v_cvt_pk_bf16_f32 v130, v92, v93
	v_mov_b32_e32 v80, v93
	v_mov_b32_e32 v81, v94
	v_mov_b32_e32 v93, v95
	v_pk_add_f32 v[80:81], v[80:81], v[92:93]
	v_cvt_pk_bf16_f32 v131, v94, v95
	v_add_f32_e32 v80, v80, v81
	v_add_f32_e32 v104, v80, v82
	ds_read_b64_tr_b16 v[80:81], v207 offset:24576
	ds_read_b64_tr_b16 v[82:83], v207 offset:25088
	ds_read_b64_tr_b16 v[84:85], v207 offset:28672
	ds_read_b64_tr_b16 v[86:87], v207 offset:29184
	ds_read_b64_tr_b16 v[88:89], v207 offset:25600
	ds_read_b64_tr_b16 v[90:91], v207 offset:26112
	ds_read_b64_tr_b16 v[92:93], v207 offset:29696
	ds_read_b64_tr_b16 v[94:95], v207 offset:30208
	v_add_f32_e32 v105, v197, v180
	s_waitcnt lgkmcnt(6)
	v_mfma_f32_32x32x16_bf16 v[16:31], v[80:83], v[140:143], v[16:31]
	v_exp_f32_e32 v48, v48
	v_exp_f32_e32 v49, v49
	v_exp_f32_e32 v50, v50
	v_exp_f32_e32 v51, v51
	s_waitcnt lgkmcnt(4)
	v_mfma_f32_32x32x16_bf16 v[0:15], v[84:87], v[140:143], v[0:15]
	v_exp_f32_e32 v52, v52
	v_exp_f32_e32 v53, v53
	v_exp_f32_e32 v54, v54
	v_exp_f32_e32 v55, v55
	ds_read_b64_tr_b16 v[80:81], v207 offset:26624
	ds_read_b64_tr_b16 v[82:83], v207 offset:27136
	ds_read_b64_tr_b16 v[84:85], v207 offset:27648
	ds_read_b64_tr_b16 v[86:87], v207 offset:28160
	ds_read_b64_tr_b16 v[96:97], v207 offset:30720
	ds_read_b64_tr_b16 v[98:99], v207 offset:31232
	ds_read_b64_tr_b16 v[100:101], v207 offset:31744
	ds_read_b64_tr_b16 v[102:103], v207 offset:32256
	s_waitcnt lgkmcnt(10)
	v_mfma_f32_32x32x16_bf16 v[16:31], v[88:91], v[136:139], v[16:31]
	v_exp_f32_e32 v56, v56
	v_exp_f32_e32 v57, v57
	v_exp_f32_e32 v58, v58
	v_exp_f32_e32 v59, v59
	s_waitcnt lgkmcnt(8)
	v_mfma_f32_32x32x16_bf16 v[0:15], v[92:95], v[136:139], v[0:15]
	v_exp_f32_e32 v60, v60
	v_exp_f32_e32 v61, v61
	v_exp_f32_e32 v62, v62
	v_exp_f32_e32 v63, v63
	s_waitcnt lgkmcnt(6)
	v_mfma_f32_32x32x16_bf16 v[16:31], v[80:83], v[132:135], v[16:31]
	v_exp_f32_e32 v64, v64
	v_exp_f32_e32 v65, v65
	v_exp_f32_e32 v66, v66
	v_exp_f32_e32 v67, v67
	s_waitcnt lgkmcnt(2)
	v_mfma_f32_32x32x16_bf16 v[0:15], v[96:99], v[132:135], v[0:15]
	v_exp_f32_e32 v68, v68
	v_exp_f32_e32 v69, v69
	v_exp_f32_e32 v70, v70
	v_exp_f32_e32 v71, v71
	v_mfma_f32_32x32x16_bf16 v[16:31], v[84:87], v[128:131], v[16:31]
	v_exp_f32_e32 v72, v72
	v_exp_f32_e32 v73, v73
	v_exp_f32_e32 v74, v74
	v_exp_f32_e32 v75, v75
	s_waitcnt lgkmcnt(0)
	v_mfma_f32_32x32x16_bf16 v[0:15], v[100:103], v[128:131], v[0:15]
	v_exp_f32_e32 v76, v76
	v_exp_f32_e32 v77, v77
	v_exp_f32_e32 v78, v78
	v_exp_f32_e32 v79, v79
	s_add_i32 s16, s16, 0x8000
	v_add_f32_e32 v197, v105, v104
	s_waitcnt vmcnt(1)
	ds_write_b128 v202, v[160:163] offset:8192
	s_waitcnt vmcnt(0)
	ds_write_b128 v196, v[164:167] offset:16384
	s_cmp_lt_u32 s17, s15
	v_mov_b32_e32 v162, v64
	v_mov_b32_e32 v164, v65
	v_mov_b32_e32 v165, v66
	v_mov_b32_e32 v163, v67
	v_mov_b32_e32 v156, v68
	v_mov_b32_e32 v160, v69
	v_mov_b32_e32 v161, v70
	v_mov_b32_e32 v157, v71
	v_mov_b32_e32 v136, v72
	v_mov_b32_e32 v140, v73
	v_mov_b32_e32 v141, v74
	v_mov_b32_e32 v137, v75
	v_mov_b32_e32 v128, v76
	v_mov_b32_e32 v132, v77
	v_mov_b32_e32 v133, v78
	v_mov_b32_e32 v129, v79
	s_waitcnt lgkmcnt(0)
	s_barrier
	s_cbranch_scc1 .LBB0_199
	s_setprio 0
	v_add_u32_e32 v80, s16, v204
	global_load_dwordx4 v[96:99], v80, s[56:57]
	ds_read_b128 v[100:103], v201 offset:8192
	ds_read_b128 v[104:107], v201 offset:12288
	ds_read_b128 v[108:111], v206 offset:8192
	ds_read_b128 v[128:131], v206 offset:12288
	s_setprio 1
	s_waitcnt lgkmcnt(3)
	v_mfma_f32_32x32x16_bf16 v[80:95], v[100:103], v[120:123], v[32:47]
	s_setprio 0
	v_cvt_pk_bf16_f32 v100, v48, v49
	v_add_f32_e32 v48, v48, v49
	v_add_f32_e32 v49, v50, v51
	v_add_f32_e32 v48, v48, v49
	v_cvt_pk_bf16_f32 v101, v50, v51
	v_add_f32_e32 v48, 0, v48
	s_setprio 1
	s_waitcnt lgkmcnt(2)
	v_mfma_f32_32x32x16_bf16 v[32:47], v[104:107], v[120:123], v[32:47]
	s_setprio 0
	v_add_f32_e32 v49, v52, v53
	v_add_f32_e32 v50, v54, v55
	v_add_f32_e32 v49, v49, v50
	v_cvt_pk_bf16_f32 v102, v52, v53
	v_cvt_pk_bf16_f32 v103, v54, v55
	v_add_f32_e32 v132, v49, v48
	ds_read_b128 v[48:51], v203 offset:8192
	ds_read_b128 v[52:55], v203 offset:12288
	ds_read_b128 v[104:107], v205 offset:8192
	ds_read_b128 v[120:123], v205 offset:12288
	s_setprio 1
	s_waitcnt lgkmcnt(5)
	v_mfma_f32_32x32x16_bf16 v[80:95], v[108:111], v[116:119], v[80:95]
	s_setprio 0
	v_cvt_pk_bf16_f32 v108, v56, v57
	v_add_f32_e32 v56, v56, v57
	v_add_f32_e32 v57, v58, v59
	v_add_f32_e32 v56, v56, v57
	v_cvt_pk_bf16_f32 v109, v58, v59
	v_add_f32_e32 v56, v56, v132
	s_setprio 1
	s_waitcnt lgkmcnt(4)
	v_mfma_f32_32x32x16_bf16 v[32:47], v[128:131], v[116:119], v[32:47]
	s_setprio 0
	v_add_f32_e32 v57, v60, v61
	v_add_f32_e32 v58, v62, v63
	v_add_f32_e32 v57, v57, v58
	v_cvt_pk_bf16_f32 v110, v60, v61
	v_cvt_pk_bf16_f32 v111, v62, v63
	v_add_f32_e32 v56, v57, v56
	s_setprio 1
	s_waitcnt lgkmcnt(3)
	v_mfma_f32_32x32x16_bf16 v[80:95], v[48:51], v[112:115], v[80:95]
	s_setprio 0
	v_add_f32_e32 v50, v64, v65
	v_add_f32_e32 v51, v66, v67
	v_add_f32_e32 v50, v50, v51
	v_cvt_pk_bf16_f32 v48, v64, v65
	v_cvt_pk_bf16_f32 v49, v66, v67
	v_add_f32_e32 v56, v50, v56
	s_setprio 1
	s_waitcnt lgkmcnt(2)
	v_mfma_f32_32x32x16_bf16 v[32:47], v[52:55], v[112:115], v[32:47]
	s_setprio 0
	v_add_f32_e32 v52, v68, v69
	v_add_f32_e32 v53, v70, v71
	v_add_f32_e32 v52, v52, v53
	v_cvt_pk_bf16_f32 v50, v68, v69
	v_cvt_pk_bf16_f32 v51, v70, v71
	v_add_f32_e32 v56, v52, v56
	s_setprio 1
	s_waitcnt lgkmcnt(1)
	v_mfma_f32_32x32x16_bf16 v[80:95], v[104:107], v[124:127], v[80:95]
	s_setprio 0
	v_cvt_pk_bf16_f32 v52, v72, v73
	v_mov_b32_e32 v54, v73
	v_mov_b32_e32 v55, v74
	v_mov_b32_e32 v73, v75
	v_pk_add_f32 v[54:55], v[54:55], v[72:73]
	v_cvt_pk_bf16_f32 v53, v74, v75
	v_add_f32_e32 v54, v54, v55
	v_add_f32_e32 v58, v54, v56
	s_setprio 1
	s_waitcnt lgkmcnt(0)
	v_mfma_f32_32x32x16_bf16 v[32:47], v[120:123], v[124:127], v[32:47]
	s_setprio 0
	v_cvt_pk_bf16_f32 v54, v76, v77
	v_mov_b32_e32 v56, v77
	v_mov_b32_e32 v57, v78
	v_mov_b32_e32 v77, v79
	v_pk_add_f32 v[56:57], v[56:57], v[76:77]
	v_cvt_pk_bf16_f32 v55, v78, v79
	v_add_f32_e32 v56, v56, v57
	v_add_f32_e32 v104, v56, v58
	v_lshlrev_b32_e32 v56, 8, v193
	v_or3_b32 v105, v56, v200, v199
	ds_read_b64_tr_b16 v[56:57], v105 offset:16384
	ds_read_b64_tr_b16 v[58:59], v105 offset:16896
	ds_read_b64_tr_b16 v[60:61], v105 offset:17408
	ds_read_b64_tr_b16 v[62:63], v105 offset:17920
	ds_read_b64_tr_b16 v[64:65], v105 offset:20480
	ds_read_b64_tr_b16 v[66:67], v105 offset:20992
	ds_read_b64_tr_b16 v[68:69], v105 offset:21504
	ds_read_b64_tr_b16 v[70:71], v105 offset:22016
	s_setprio 1
	s_waitcnt lgkmcnt(6)
	v_mfma_f32_32x32x16_bf16 v[16:31], v[56:59], v[100:103], v[16:31]
	s_setprio 0
	v_exp_f32_e32 v80, v80
	v_exp_f32_e32 v81, v81
	v_exp_f32_e32 v82, v82
	v_exp_f32_e32 v83, v83
	s_setprio 1
	s_waitcnt lgkmcnt(2)
	v_mfma_f32_32x32x16_bf16 v[0:15], v[64:67], v[100:103], v[0:15]
	s_setprio 0
	v_exp_f32_e32 v84, v84
	v_exp_f32_e32 v85, v85
	v_exp_f32_e32 v86, v86
	v_exp_f32_e32 v87, v87
	ds_read_b64_tr_b16 v[56:57], v105 offset:18432
	ds_read_b64_tr_b16 v[58:59], v105 offset:18944
	ds_read_b64_tr_b16 v[64:65], v105 offset:19456
	ds_read_b64_tr_b16 v[66:67], v105 offset:19968
	ds_read_b64_tr_b16 v[72:73], v105 offset:22528
	ds_read_b64_tr_b16 v[74:75], v105 offset:23040
	ds_read_b64_tr_b16 v[76:77], v105 offset:23552
	ds_read_b64_tr_b16 v[78:79], v105 offset:24064
	s_setprio 1
	v_mfma_f32_32x32x16_bf16 v[16:31], v[60:63], v[108:111], v[16:31]
	s_setprio 0
	v_exp_f32_e32 v88, v88
	v_exp_f32_e32 v89, v89
	v_exp_f32_e32 v90, v90
	v_exp_f32_e32 v91, v91
	s_setprio 1
	s_waitcnt lgkmcnt(8)
	v_mfma_f32_32x32x16_bf16 v[0:15], v[68:71], v[108:111], v[0:15]
	s_setprio 0
	v_exp_f32_e32 v92, v92
	v_exp_f32_e32 v93, v93
	v_exp_f32_e32 v94, v94
	v_exp_f32_e32 v95, v95
	s_setprio 1
	s_waitcnt lgkmcnt(6)
	v_mfma_f32_32x32x16_bf16 v[16:31], v[56:59], v[48:51], v[16:31]
	s_setprio 0
	v_exp_f32_e32 v32, v32
	v_exp_f32_e32 v33, v33
	v_exp_f32_e32 v34, v34
	v_exp_f32_e32 v35, v35
	s_setprio 1
	s_waitcnt lgkmcnt(2)
	v_mfma_f32_32x32x16_bf16 v[0:15], v[72:75], v[48:51], v[0:15]
	s_setprio 0
	v_exp_f32_e32 v36, v36
	v_exp_f32_e32 v37, v37
	v_exp_f32_e32 v38, v38
	v_exp_f32_e32 v39, v39
	s_setprio 1
	v_mfma_f32_32x32x16_bf16 v[16:31], v[64:67], v[52:55], v[16:31]
	s_setprio 0
	v_exp_f32_e32 v40, v40
	v_exp_f32_e32 v41, v41
	v_exp_f32_e32 v42, v42
	v_exp_f32_e32 v43, v43
	s_setprio 1
	s_waitcnt lgkmcnt(0)
	v_mfma_f32_32x32x16_bf16 v[0:15], v[76:79], v[52:55], v[0:15]
	s_setprio 0
	v_exp_f32_e32 v44, v44
	v_exp_f32_e32 v45, v45
	v_exp_f32_e32 v46, v46
	v_exp_f32_e32 v47, v47
	s_waitcnt vmcnt(0)
	ds_write_b128 v196, v[96:99] offset:24576
	s_waitcnt lgkmcnt(0)
	s_barrier
	v_add_f32_e32 v50, v80, v81
	v_add_f32_e32 v51, v82, v83
	v_add_f32_e32 v50, v50, v51
	v_cvt_pk_bf16_f32 v48, v80, v81
	v_cvt_pk_bf16_f32 v49, v82, v83
	v_add_f32_e32 v52, 0, v50
	v_add_f32_e32 v53, v84, v85
	v_add_f32_e32 v54, v86, v87
	v_add_f32_e32 v53, v53, v54
	v_cvt_pk_bf16_f32 v50, v84, v85
	v_cvt_pk_bf16_f32 v51, v86, v87
	v_add_f32_e32 v54, v53, v52
	v_add_f32_e32 v55, v88, v89
	v_add_f32_e32 v56, v90, v91
	v_add_f32_e32 v55, v55, v56
	v_cvt_pk_bf16_f32 v52, v88, v89
	v_cvt_pk_bf16_f32 v53, v90, v91
	v_add_f32_e32 v56, v55, v54
	v_add_f32_e32 v57, v92, v93
	v_add_f32_e32 v58, v94, v95
	v_add_f32_e32 v57, v57, v58
	v_cvt_pk_bf16_f32 v54, v92, v93
	v_cvt_pk_bf16_f32 v55, v94, v95
	v_add_f32_e32 v58, v57, v56
	v_cvt_pk_bf16_f32 v56, v32, v33
	v_add_f32_e32 v32, v32, v33
	v_add_f32_e32 v33, v34, v35
	v_add_f32_e32 v32, v32, v33
	v_cvt_pk_bf16_f32 v57, v34, v35
	v_add_f32_e32 v34, v32, v58
	s_nop 0
	v_cvt_pk_bf16_f32 v58, v36, v37
	v_mov_b32_e32 v32, v37
	v_mov_b32_e32 v33, v38
	v_mov_b32_e32 v37, v39
	v_pk_add_f32 v[32:33], v[32:33], v[36:37]
	v_cvt_pk_bf16_f32 v59, v38, v39
	v_add_f32_e32 v32, v32, v33
	v_add_f32_e32 v36, v32, v34
	v_cvt_pk_bf16_f32 v32, v40, v41
	v_mov_b32_e32 v34, v41
	v_mov_b32_e32 v35, v42
	v_mov_b32_e32 v41, v43
	v_pk_add_f32 v[34:35], v[34:35], v[40:41]
	v_cvt_pk_bf16_f32 v33, v42, v43
	v_add_f32_e32 v34, v34, v35
	v_add_f32_e32 v38, v34, v36
	s_nop 0
	v_cvt_pk_bf16_f32 v34, v44, v45
	v_mov_b32_e32 v36, v45
	v_mov_b32_e32 v37, v46
	v_mov_b32_e32 v45, v47
	v_pk_add_f32 v[36:37], v[36:37], v[44:45]
	v_cvt_pk_bf16_f32 v35, v46, v47
	v_add_f32_e32 v36, v36, v37
	v_add_f32_e32 v68, v36, v38
	ds_read_b64_tr_b16 v[36:37], v105 offset:24576
	ds_read_b64_tr_b16 v[38:39], v105 offset:25088
	ds_read_b64_tr_b16 v[40:41], v105 offset:25600
	ds_read_b64_tr_b16 v[42:43], v105 offset:26112
	ds_read_b64_tr_b16 v[44:45], v105 offset:28672
	ds_read_b64_tr_b16 v[46:47], v105 offset:29184
	ds_read_b64_tr_b16 v[60:61], v105 offset:29696
	ds_read_b64_tr_b16 v[62:63], v105 offset:30208
	s_setprio 1
	s_waitcnt lgkmcnt(6)
	v_mfma_f32_32x32x16_bf16 v[16:31], v[36:39], v[48:51], v[16:31]
	s_setprio 0
	s_setprio 1
	s_waitcnt lgkmcnt(2)
	v_mfma_f32_32x32x16_bf16 v[0:15], v[44:47], v[48:51], v[0:15]
	s_setprio 0
	ds_read_b64_tr_b16 v[36:37], v105 offset:26624
	ds_read_b64_tr_b16 v[38:39], v105 offset:27136
	ds_read_b64_tr_b16 v[44:45], v105 offset:27648
	ds_read_b64_tr_b16 v[46:47], v105 offset:28160
	ds_read_b64_tr_b16 v[48:49], v105 offset:30720
	ds_read_b64_tr_b16 v[50:51], v105 offset:31232
	ds_read_b64_tr_b16 v[64:65], v105 offset:31744
	ds_read_b64_tr_b16 v[66:67], v105 offset:32256
	s_setprio 1
	v_mfma_f32_32x32x16_bf16 v[16:31], v[40:43], v[52:55], v[16:31]
	s_setprio 0
	s_setprio 1
	s_waitcnt lgkmcnt(8)
	v_mfma_f32_32x32x16_bf16 v[0:15], v[60:63], v[52:55], v[0:15]
	s_setprio 0
	s_setprio 1
	s_waitcnt lgkmcnt(6)
	v_mfma_f32_32x32x16_bf16 v[16:31], v[36:39], v[56:59], v[16:31]
	s_setprio 0
	s_setprio 1
	s_waitcnt lgkmcnt(2)
	v_mfma_f32_32x32x16_bf16 v[0:15], v[48:51], v[56:59], v[0:15]
	s_setprio 0
	s_setprio 1
	v_mfma_f32_32x32x16_bf16 v[16:31], v[44:47], v[32:35], v[16:31]
	s_setprio 0
	s_setprio 1
	s_waitcnt lgkmcnt(0)
	v_mfma_f32_32x32x16_bf16 v[0:15], v[64:67], v[32:35], v[0:15]
	s_setprio 0
	v_add_f32_e32 v32, v197, v104
	v_add_f32_e32 v32, v32, v68
	ds_bpermute_b32 v33, v168, v32
	s_lshl_b32 s30, s5, 1
	s_waitcnt lgkmcnt(0)
	s_barrier
	v_add_f32_e32 v32, v32, v33
	v_div_scale_f32 v33, s[16:17], v32, v32, 1.0
	v_rcp_f32_e32 v34, v33
	v_div_scale_f32 v35, vcc, 1.0, v32, 1.0
	s_mov_b32 s76, 0
	v_fma_f32 v36, -v33, v34, 1.0
	v_fmac_f32_e32 v34, v36, v34
	v_mul_f32_e32 v36, v35, v34
	v_fma_f32 v37, -v33, v36, v35
	v_fmac_f32_e32 v36, v37, v34
	v_fma_f32 v33, -v33, v36, v35
	v_div_fmas_f32 v33, v33, v34, v36
	v_div_fixup_f32 v32, v33, v32, 1.0
	v_pk_mul_f32 v[26:27], v[32:33], v[26:27] op_sel_hi:[0,1]
	v_pk_mul_f32 v[10:11], v[32:33], v[10:11] op_sel_hi:[0,1]
	v_pk_mul_f32 v[28:29], v[32:33], v[28:29] op_sel_hi:[0,1]
	v_pk_mul_f32 v[12:13], v[32:33], v[12:13] op_sel_hi:[0,1]
	v_pk_mul_f32 v[30:31], v[32:33], v[30:31] op_sel_hi:[0,1]
	v_pk_mul_f32 v[14:15], v[32:33], v[14:15] op_sel_hi:[0,1]
	v_lshl_or_b32 v33, v194, 5, v195
	v_pk_mul_f32 v[0:1], v[32:33], v[0:1] op_sel_hi:[0,1]
	v_pk_mul_f32 v[16:17], v[32:33], v[16:17] op_sel_hi:[0,1]
	v_pk_mul_f32 v[2:3], v[32:33], v[2:3] op_sel_hi:[0,1]
	v_pk_mul_f32 v[44:45], v[0:1], v[0:1]
	v_pk_mul_f32 v[18:19], v[32:33], v[18:19] op_sel_hi:[0,1]
	v_pk_mul_f32 v[42:43], v[2:3], v[2:3]
	v_pk_fma_f32 v[44:45], v[16:17], v[16:17], v[44:45]
	v_pk_fma_f32 v[42:43], v[18:19], v[18:19], v[42:43]
	v_pk_mul_f32 v[4:5], v[32:33], v[4:5] op_sel_hi:[0,1]
	v_add_f32_e32 v41, v44, v45
	v_pk_mul_f32 v[20:21], v[32:33], v[20:21] op_sel_hi:[0,1]
	v_pk_mul_f32 v[48:49], v[4:5], v[4:5]
	v_add_f32_e32 v41, v41, v42
	v_pk_mul_f32 v[6:7], v[32:33], v[6:7] op_sel_hi:[0,1]
	v_pk_fma_f32 v[48:49], v[20:21], v[20:21], v[48:49]
	v_add_f32_e32 v41, v41, v43
	v_pk_mul_f32 v[22:23], v[32:33], v[22:23] op_sel_hi:[0,1]
	v_pk_mul_f32 v[46:47], v[6:7], v[6:7]
	v_add_f32_e32 v41, v41, v48
	v_pk_fma_f32 v[46:47], v[22:23], v[22:23], v[46:47]
	v_pk_mul_f32 v[8:9], v[32:33], v[8:9] op_sel_hi:[0,1]
	v_add_f32_e32 v41, v41, v49
	v_add_u32_e32 v40, s14, v33
	v_pk_mul_f32 v[24:25], v[32:33], v[24:25] op_sel_hi:[0,1]
	v_pk_mul_f32 v[32:33], v[8:9], v[8:9]
	v_add_f32_e32 v41, v41, v46
	v_pk_fma_f32 v[32:33], v[24:25], v[24:25], v[32:33]
	v_add_f32_e32 v41, v41, v47
	v_pk_mul_f32 v[34:35], v[10:11], v[10:11]
	v_add_f32_e32 v32, v41, v32
	v_pk_fma_f32 v[34:35], v[26:27], v[26:27], v[34:35]
	v_add_f32_e32 v32, v32, v33
	v_pk_mul_f32 v[36:37], v[12:13], v[12:13]
	v_add_f32_e32 v32, v32, v34
	v_pk_fma_f32 v[36:37], v[28:29], v[28:29], v[36:37]
	v_add_f32_e32 v32, v32, v35
	v_pk_mul_f32 v[38:39], v[14:15], v[14:15]
	v_add_f32_e32 v32, v32, v36
	v_pk_fma_f32 v[38:39], v[30:31], v[30:31], v[38:39]
	v_add_f32_e32 v32, v32, v37
	v_add_f32_e32 v32, v32, v38
	v_add_f32_e32 v34, v32, v39
	ds_bpermute_b32 v35, v168, v34
	v_ashrrev_i32_e32 v41, 31, v40
	v_lshlrev_b64 v[32:33], 11, v[40:41]
	v_lshl_add_u64 v[32:33], s[46:47], 0, v[32:33]
	v_lshl_add_u64 v[32:33], v[32:33], 0, s[30:31]
	s_waitcnt lgkmcnt(0)
	v_add_f32_e32 v34, v34, v35
	v_fmamk_f32 v34, v34, 0x3c800000, v172
	v_mul_f32_e32 v35, 0x4b800000, v34
	v_cmp_gt_f32_e32 vcc, s4, v34
	v_lshlrev_b32_e32 v168, 3, v193
	v_lshl_add_u64 v[32:33], v[32:33], 0, v[168:169]
	v_cndmask_b32_e32 v34, v34, v35, vcc
	v_rsq_f32_e32 v34, v34
	s_mov_b32 s78, 0
	s_mov_b32 s80, 0
	s_mov_b32 s82, 0
	v_mul_f32_e32 v35, 0x45800000, v34
	v_cndmask_b32_e32 v34, v34, v35, vcc
	v_pk_mul_f32 v[16:17], v[34:35], v[16:17] op_sel_hi:[0,1]
	v_pk_mul_f32 v[18:19], v[34:35], v[18:19] op_sel_hi:[0,1]
	v_pk_mul_f32 v[0:1], v[34:35], v[0:1] op_sel_hi:[0,1]
	v_pk_mul_f32 v[2:3], v[34:35], v[2:3] op_sel_hi:[0,1]
	v_cvt_pk_bf16_f32 v16, v16, v17
	v_cvt_pk_bf16_f32 v17, v18, v19
	v_cvt_pk_bf16_f32 v0, v0, v1
	v_cvt_pk_bf16_f32 v1, v2, v3
	global_store_dwordx2 v[32:33], v[16:17], off offset:512
	v_pk_mul_f32 v[16:17], v[34:35], v[20:21] op_sel_hi:[0,1]
	v_pk_mul_f32 v[18:19], v[34:35], v[22:23] op_sel_hi:[0,1]
	global_store_dwordx2 v[32:33], v[0:1], off offset:576
	v_pk_mul_f32 v[0:1], v[34:35], v[4:5] op_sel_hi:[0,1]
	v_pk_mul_f32 v[2:3], v[34:35], v[6:7] op_sel_hi:[0,1]
	v_cvt_pk_bf16_f32 v16, v16, v17
	v_cvt_pk_bf16_f32 v17, v18, v19
	v_cvt_pk_bf16_f32 v0, v0, v1
	v_cvt_pk_bf16_f32 v1, v2, v3
	global_store_dwordx2 v[32:33], v[16:17], off offset:528
	v_pk_mul_f32 v[16:17], v[34:35], v[24:25] op_sel_hi:[0,1]
	v_pk_mul_f32 v[18:19], v[34:35], v[26:27] op_sel_hi:[0,1]
	global_store_dwordx2 v[32:33], v[0:1], off offset:592
	v_pk_mul_f32 v[0:1], v[34:35], v[8:9] op_sel_hi:[0,1]
	v_pk_mul_f32 v[2:3], v[34:35], v[10:11] op_sel_hi:[0,1]
	v_cvt_pk_bf16_f32 v16, v16, v17
	v_cvt_pk_bf16_f32 v17, v18, v19
	v_cvt_pk_bf16_f32 v0, v0, v1
	v_cvt_pk_bf16_f32 v1, v2, v3
	global_store_dwordx2 v[32:33], v[16:17], off offset:544
	v_pk_mul_f32 v[16:17], v[34:35], v[28:29] op_sel_hi:[0,1]
	v_pk_mul_f32 v[18:19], v[34:35], v[30:31] op_sel_hi:[0,1]
	global_store_dwordx2 v[32:33], v[0:1], off offset:608
	v_pk_mul_f32 v[0:1], v[34:35], v[12:13] op_sel_hi:[0,1]
	v_pk_mul_f32 v[2:3], v[34:35], v[14:15] op_sel_hi:[0,1]
	s_mov_b32 s68, 0
	s_mov_b32 s70, 0
	s_mov_b32 s72, 0
	v_readlane_b32 s74, v254, 52
	v_cvt_pk_bf16_f32 v16, v16, v17
	v_cvt_pk_bf16_f32 v17, v18, v19
	v_cvt_pk_bf16_f32 v0, v0, v1
	v_cvt_pk_bf16_f32 v1, v2, v3
	s_mov_b32 s77, 0x40732000
	s_mov_b32 s79, 0x40756000
	s_mov_b32 s81, 0x4077c000
	s_mov_b32 s83, 0x407a4000
	s_mov_b32 s69, 0x407ce000
	s_mov_b32 s71, 0x407fa000
	s_mov_b32 s73, 0x40814000
	v_readlane_b32 s75, v254, 53
	global_store_dwordx2 v[32:33], v[16:17], off offset:560
	global_store_dwordx2 v[32:33], v[0:1], off offset:624
	s_branch .LBB0_106

.LBB0_209:
	s_and_b32 s55, s24, 3
	v_and_b32_e32 v7, 15, v6
	v_and_b32_e32 v135, 48, v6
	v_lshlrev_b32_e32 v6, 2, v6
	v_lshl_add_u64 v[8:9], s[40:41], 0, v[168:169]
	v_mov_b32_e32 v129, v169
	v_lshl_or_b32 v134, s27, 6, v7
	v_lshl_or_b32 v7, v7, 6, v135
	v_and_b32_e32 v6, 32, v6
	s_lshl_b32 s24, s27, 13
	s_lshl_b32 s27, s55, 12
	s_add_i32 s56, s16, 0x18000
	v_lshl_add_u64 v[10:11], s[40:41], 0, v[128:129]
	v_bitop3_b32 v136, v7, s27, v6 bitop3:0xde
	v_bitop3_b32 v137, v7, s24, v6 bitop3:0xde
	v_lshl_add_u64 v[6:7], v[8:9], 0, s[34:35]
	s_mov_b32 m0, s56
	s_add_i32 s85, s16, 0x1a000
	v_lshl_add_u64 v[12:13], s[42:43], 0, v[168:169]
	s_and_b32 s57, s62, 7
	global_load_lds_dwordx4 v[6:7], off
	v_lshl_add_u64 v[6:7], v[10:11], 0, s[34:35]
	s_mov_b32 m0, s85
	s_add_i32 s86, s16, 0x8000
	s_add_i32 s87, s16, 0xa000
	v_lshl_add_u64 v[14:15], s[42:43], 0, v[128:129]
	global_load_lds_dwordx4 v[6:7], off
	v_lshl_add_u64 v[6:7], v[12:13], 0, s[34:35]
	s_mov_b32 m0, s86
	s_add_u32 s36, s40, 0x40080
	global_load_lds_dwordx4 v[6:7], off
	v_lshl_add_u64 v[6:7], v[14:15], 0, s[34:35]
	s_mov_b32 m0, s87
	s_addc_u32 s37, s41, 0
	s_add_i32 s90, s16, 0x1c000
	global_load_lds_dwordx4 v[6:7], off
	v_lshl_add_u64 v[6:7], s[36:37], 0, v[168:169]
	s_mov_b32 m0, s90
	s_add_i32 s24, s16, 0x1e000
	global_load_lds_dwordx4 v[6:7], off
	v_lshl_add_u64 v[6:7], s[36:37], 0, v[128:129]
	s_mov_b32 m0, s24
	s_add_i32 s26, s26, s57
	global_load_lds_dwordx4 v[6:7], off
	s_waitcnt vmcnt(8)
	s_barrier
	s_ashr_i32 s27, s26, 31
	s_lshl_b64 s[26:27], s[26:27], 19
	v_lshlrev_b32_e32 v6, 14, v0
	s_add_u32 s60, s74, s26
	v_and_b32_e32 v6, 0xffff8000, v6
	s_addc_u32 s91, s75, s27
	v_lshl_add_u32 v1, v1, 11, v6
	v_and_b32_e32 v0, 1, v0
	v_lshl_or_b32 v0, v0, 6, v1
	s_add_u32 s26, s18, s26
	v_lshl_add_u32 v0, v3, 1, v0
	v_mov_b32_e32 v1, v169
	s_addc_u32 s27, s19, s27
	v_lshl_add_u64 v[130:131], s[26:27], 0, v[0:1]
	v_lshlrev_b32_e32 v0, 14, v2
	v_and_b32_e32 v0, 0xffff8000, v0
	v_lshl_add_u32 v0, v4, 11, v0
	v_and_b32_e32 v1, 1, v2
	v_lshl_or_b32 v0, v1, 6, v0
	s_waitcnt vmcnt(6)
	v_lshl_add_u32 v0, v5, 1, v0
	v_mov_b32_e32 v1, v169
	v_lshl_add_u64 v[132:133], s[26:27], 0, v[0:1]
	s_add_u32 s92, s30, s14
	v_mov_b32_e32 v0, 0
	s_addc_u32 s93, s61, s15
	s_mov_b32 s94, -2
	s_mov_b64 s[44:45], 0
	v_mov_b32_e32 v1, v0
	v_mov_b32_e32 v2, v0
	v_mov_b32_e32 v3, v0
	v_mov_b32_e32 v4, v0
	v_mov_b32_e32 v5, v0
	v_mov_b32_e32 v6, v0
	v_mov_b32_e32 v7, v0
	v_mov_b32_e32 v8, v0
	v_mov_b32_e32 v9, v0
	v_mov_b32_e32 v10, v0
	v_mov_b32_e32 v11, v0
	v_mov_b32_e32 v12, v0
	v_mov_b32_e32 v13, v0
	v_mov_b32_e32 v14, v0
	v_mov_b32_e32 v15, v0
	v_mov_b32_e32 v16, v0
	v_mov_b32_e32 v17, v0
	v_mov_b32_e32 v18, v0
	v_mov_b32_e32 v19, v0
	v_mov_b32_e32 v20, v0
	v_mov_b32_e32 v21, v0
	v_mov_b32_e32 v22, v0
	v_mov_b32_e32 v23, v0
	v_mov_b32_e32 v24, v0
	v_mov_b32_e32 v25, v0
	v_mov_b32_e32 v26, v0
	v_mov_b32_e32 v27, v0
	v_mov_b32_e32 v28, v0
	v_mov_b32_e32 v29, v0
	v_mov_b32_e32 v30, v0
	v_mov_b32_e32 v31, v0
	v_mov_b32_e32 v32, v0
	v_mov_b32_e32 v33, v0
	v_mov_b32_e32 v34, v0
	v_mov_b32_e32 v35, v0
	v_mov_b32_e32 v36, v0
	v_mov_b32_e32 v37, v0
	v_mov_b32_e32 v38, v0
	v_mov_b32_e32 v39, v0
	v_mov_b32_e32 v40, v0
	v_mov_b32_e32 v41, v0
	v_mov_b32_e32 v42, v0
	v_mov_b32_e32 v43, v0
	v_mov_b32_e32 v44, v0
	v_mov_b32_e32 v45, v0
	v_mov_b32_e32 v46, v0
	v_mov_b32_e32 v47, v0
	v_mov_b32_e32 v48, v0
	v_mov_b32_e32 v49, v0
	v_mov_b32_e32 v50, v0
	v_mov_b32_e32 v51, v0
	v_mov_b32_e32 v52, v0
	v_mov_b32_e32 v53, v0
	v_mov_b32_e32 v54, v0
	v_mov_b32_e32 v55, v0
	v_mov_b32_e32 v56, v0
	v_mov_b32_e32 v57, v0
	v_mov_b32_e32 v58, v0
	v_mov_b32_e32 v59, v0
	v_mov_b32_e32 v60, v0
	v_mov_b32_e32 v61, v0
	v_mov_b32_e32 v62, v0
	v_mov_b32_e32 v63, v0
	v_mov_b32_e32 v64, v0
	v_mov_b32_e32 v65, v0
	v_mov_b32_e32 v66, v0
	v_mov_b32_e32 v67, v0
	v_mov_b32_e32 v68, v0
	v_mov_b32_e32 v69, v0
	v_mov_b32_e32 v70, v0
	v_mov_b32_e32 v71, v0
	v_mov_b32_e32 v72, v0
	v_mov_b32_e32 v73, v0
	v_mov_b32_e32 v74, v0
	v_mov_b32_e32 v75, v0
	v_mov_b32_e32 v76, v0
	v_mov_b32_e32 v77, v0
	v_mov_b32_e32 v78, v0
	v_mov_b32_e32 v79, v0
	v_mov_b32_e32 v80, v0
	v_mov_b32_e32 v81, v0
	v_mov_b32_e32 v82, v0
	v_mov_b32_e32 v83, v0
	v_mov_b32_e32 v84, v0
	v_mov_b32_e32 v85, v0
	v_mov_b32_e32 v86, v0
	v_mov_b32_e32 v87, v0
	v_mov_b32_e32 v88, v0
	v_mov_b32_e32 v89, v0
	v_mov_b32_e32 v90, v0
	v_mov_b32_e32 v91, v0
	v_mov_b32_e32 v92, v0
	v_mov_b32_e32 v93, v0
	v_mov_b32_e32 v94, v0
	v_mov_b32_e32 v95, v0
	v_mov_b32_e32 v96, v0
	v_mov_b32_e32 v97, v0
	v_mov_b32_e32 v98, v0
	v_mov_b32_e32 v99, v0
	v_mov_b32_e32 v100, v0
	v_mov_b32_e32 v101, v0
	v_mov_b32_e32 v102, v0
	v_mov_b32_e32 v103, v0
	v_mov_b32_e32 v104, v0
	v_mov_b32_e32 v105, v0
	v_mov_b32_e32 v106, v0
	v_mov_b32_e32 v107, v0
	v_mov_b32_e32 v108, v0
	v_mov_b32_e32 v109, v0
	v_mov_b32_e32 v110, v0
	v_mov_b32_e32 v111, v0
	v_mov_b32_e32 v112, v0
	v_mov_b32_e32 v113, v0
	v_mov_b32_e32 v114, v0
	v_mov_b32_e32 v115, v0
	v_mov_b32_e32 v116, v0
	v_mov_b32_e32 v117, v0
	v_mov_b32_e32 v118, v0
	v_mov_b32_e32 v119, v0
	v_mov_b32_e32 v120, v0
	v_mov_b32_e32 v121, v0
	v_mov_b32_e32 v122, v0
	v_mov_b32_e32 v123, v0
	v_mov_b32_e32 v124, v0
	v_mov_b32_e32 v125, v0
	v_mov_b32_e32 v126, v0
	v_mov_b32_e32 v127, v0
	s_nop 0
	s_nop 0
	s_nop 0
	s_nop 0
	s_nop 0
	s_nop 0
	s_nop 0
	s_nop 0
	s_nop 0
	s_barrier
